# split-phase SEAM3 arrival: the 8 WGs owning a 5th G2 unit (now the sample-row tiles) arrive before it and publish via a counter; G3 logical WG ids rotated by 8
# speedup vs baseline: 1.0079x; 1.0079x over previous
.LBB0_600:
	s_cmp_gt_i32 s88, 3
	s_cselect_b64 s[2:3], -1, 0
	s_xor_b64 s[0:1], s[0:1], -1
	s_or_b64 s[0:1], s[2:3], s[0:1]
	s_and_b64 vcc, exec, s[0:1]
	s_cbranch_vccnz .LBB0_962
	v_readlane_b32 s0, v249, 0
	s_ashr_i32 s24, s96, 31
	s_ashr_i32 s25, s0, 31
	s_cmpk_lt_i32 s0, 0x408
	v_lshlrev_b32_e32 v1, 2, v188
	s_cselect_b64 s[6:7], -1, 0
	s_cmpk_gt_i32 s0, 0x407
	v_lshlrev_b32_e32 v156, 3, v188
	s_cbranch_scc1 .LBB0_619
	s_add_u32 s8, s30, 0x2ac00000
	s_movk_i32 s0, 0xff
	s_movk_i32 s2, 0x100
	s_addc_u32 s9, s31, 0
	v_cmp_lt_u32_e64 s[0:1], s0, v188
	v_cmp_gt_u32_e64 s[2:3], s2, v188
	s_and_saveexec_b64 s[10:11], s[2:3]
	s_cbranch_execz .LBB0_604
	s_lshr_b32 s4, s25, 29
	v_readlane_b32 s12, v249, 0
	s_add_i32 s4, s12, s4
	s_and_b32 s5, s4, -8
	s_sub_i32 s5, s12, s5
	s_cmp_lt_i32 s5, 0
	s_movk_i32 s12, 0x82
	s_movk_i32 s12, 0x80
	s_mul_i32 s5, s5, s12
	s_ashr_i32 s4, s4, 3
	s_add_i32 s4, s5, s4
	s_ashr_i32 s5, s4, 31
	s_lshr_b32 s5, s5, 27
	s_add_i32 s5, s4, s5
	s_ashr_i32 s12, s5, 5
	s_lshl_b32 s12, s12, 3
	s_andn2_b32 s5, s5, 31
	s_sub_i32 s13, s4, s5
	s_sub_i32 s4, 0x102, s12
	s_min_u32 s14, s4, 8
	v_cvt_f32_ubyte0_e32 v2, s14
	v_cvt_f32_i32_e32 v0, s13
	v_rcp_iflag_f32_e32 v3, v2
	s_ashr_i32 s4, s13, 30
	s_or_b32 s15, s4, 1
	v_mul_f32_e32 v3, v0, v3
	v_trunc_f32_e32 v3, v3
	v_fma_f32 v0, -v3, v2, v0
	v_cvt_i32_f32_e32 v3, v3
	v_cmp_ge_f32_e64 s[4:5], |v0|, v2
	s_and_b64 s[4:5], s[4:5], exec
	s_cselect_b32 s4, s15, 0
	v_readfirstlane_b32 s5, v3
	s_add_i32 s4, s5, s4
	s_mul_i32 s4, s4, s14
	s_sub_i32 s4, s13, s4
	s_sext_i32_i8 s4, s4
	s_add_i32 s12, s12, s4
	v_lshl_or_b32 v2, s12, 10, v1
	v_ashrrev_i32_e32 v3, 31, v2
	s_waitcnt lgkmcnt(0)
	v_lshl_add_u64 v[18:19], v[2:3], 4, s[8:9]
	global_load_dwordx4 v[2:5], v[18:19], off
	global_load_dwordx4 v[6:9], v[18:19], off offset:16
	global_load_dwordx4 v[10:13], v[18:19], off offset:32
	global_load_dwordx4 v[14:17], v[18:19], off offset:48
	v_mov_b32_e32 v0, 0x358637bd
	s_waitcnt vmcnt(0)
	v_add_f32_e32 v2, v2, v3
	v_add_f32_e32 v3, v4, v5
	v_add_f32_e32 v4, v6, v7
	v_add_f32_e32 v5, v8, v9
	v_add_f32_e32 v6, v10, v11
	v_add_f32_e32 v7, v12, v13
	v_add_f32_e32 v8, v14, v15
	v_add_f32_e32 v9, v16, v17
	v_add_f32_e32 v2, v2, v3
	v_add_f32_e32 v3, v4, v5
	v_add_f32_e32 v4, v6, v7
	v_add_f32_e32 v5, v8, v9
	v_add_f32_e32 v2, v2, v3
	v_add_f32_e32 v3, v4, v5
	v_fmamk_f32 v2, v2, 0x3b000000, v0
	v_fmac_f32_e32 v0, 0x3b000000, v3
	v_div_scale_f32 v3, s[4:5], v2, v2, v0
	v_rcp_f32_e32 v4, v3
	v_div_scale_f32 v5, vcc, v0, v2, v0
	s_mov_b32 s4, 0xf800000
	v_fma_f32 v6, -v3, v4, 1.0
	v_fmac_f32_e32 v4, v6, v4
	v_mul_f32_e32 v6, v5, v4
	v_fma_f32 v7, -v3, v6, v5
	v_fmac_f32_e32 v6, v7, v4
	v_fma_f32 v3, -v3, v6, v5
	v_div_fmas_f32 v3, v3, v4, v6
	v_div_fixup_f32 v2, v3, v2, v0
	v_mul_f32_e32 v3, 0x4f800000, v2
	v_cmp_gt_f32_e32 vcc, s4, v2
	v_mov_b32_e32 v5, 0x260
	v_add_u32_e32 v6, 0, v156
	v_cndmask_b32_e32 v2, v2, v3, vcc
	v_sqrt_f32_e32 v4, v2
	v_rsq_f32_e32 v3, v0
	v_add_u32_e32 v0, -1, v4
	v_add_u32_e32 v7, 1, v4
	v_fma_f32 v8, -v0, v4, v2
	v_fma_f32 v9, -v7, v4, v2
	v_cmp_ge_f32_e64 s[4:5], 0, v8
	s_nop 1
	v_cndmask_b32_e64 v0, v4, v0, s[4:5]
	v_cmp_lt_f32_e64 s[4:5], 0, v9
	s_nop 1
	v_cndmask_b32_e64 v0, v0, v7, s[4:5]
	v_mul_f32_e32 v4, 0x37800000, v0
	v_cndmask_b32_e32 v0, v0, v4, vcc
	v_cmp_class_f32_e32 vcc, v2, v5
	s_nop 1
	v_cndmask_b32_e32 v2, v0, v2, vcc
	v_add_u32_e32 v0, 0x20000, v6
	ds_write_b64 v0, v[2:3]
.LBB0_604:
	s_or_b64 exec, exec, s[10:11]
	v_readlane_b32 s4, v249, 0
	s_add_u32 s10, s96, s4
	s_addc_u32 s11, s24, s25
	v_mov_b64_e32 v[2:3], 0x407
	v_cmp_gt_i64_e32 vcc, s[10:11], v[2:3]
	s_cbranch_vccnz .LBB0_619
	s_and_saveexec_b64 s[12:13], s[2:3]
	s_cbranch_execz .LBB0_607
	s_ashr_i32 s4, s10, 31
	s_lshr_b32 s4, s4, 29
	s_add_i32 s4, s10, s4
	s_ashr_i32 s5, s4, 3
	s_and_b32 s4, s4, -8
	s_sub_i32 s4, s10, s4
	s_cmp_lt_i32 s4, 0
	s_movk_i32 s14, 0x82
	s_movk_i32 s14, 0x80
	s_mul_i32 s4, s4, s14
	s_add_i32 s4, s4, s5
	s_ashr_i32 s5, s4, 31
	s_lshr_b32 s5, s5, 27
	s_add_i32 s5, s4, s5
	s_ashr_i32 s14, s5, 5
	s_lshl_b32 s14, s14, 3
	s_sub_i32 s15, 0x102, s14
	s_min_i32 s15, s15, 8
	s_abs_i32 s15, s15
	v_cvt_f32_u32_e32 v0, s15
	s_sub_i32 s16, 0, s15
	s_andn2_b32 s5, s5, 31
	s_sub_i32 s4, s4, s5
	v_rcp_iflag_f32_e32 v0, v0
	s_ashr_i32 s5, s4, 31
	s_abs_i32 s4, s4
	v_mul_f32_e32 v0, 0x4f7ffffe, v0
	v_cvt_u32_f32_e32 v0, v0
	s_nop 0
	v_readfirstlane_b32 s17, v0
	s_mul_i32 s16, s16, s17
	s_mul_hi_u32 s16, s17, s16
	s_add_i32 s17, s17, s16
	s_mul_hi_u32 s16, s4, s17
	s_mul_i32 s16, s16, s15
	s_sub_i32 s4, s4, s16
	s_sub_i32 s16, s4, s15
	s_cmp_ge_u32 s4, s15
	s_cselect_b32 s4, s16, s4
	s_sub_i32 s16, s4, s15
	s_cmp_ge_u32 s4, s15
	s_cselect_b32 s4, s16, s4
	s_xor_b32 s4, s4, s5
	s_sub_i32 s4, s4, s5
	s_add_i32 s14, s14, s4
	v_lshl_or_b32 v2, s14, 10, v1
	v_ashrrev_i32_e32 v3, 31, v2
	v_lshl_add_u64 v[14:15], v[2:3], 4, s[8:9]
	global_load_dwordx4 v[2:5], v[14:15], off
	global_load_dwordx4 v[6:9], v[14:15], off offset:16
	global_load_dwordx4 v[10:13], v[14:15], off offset:32
	s_nop 0
	global_load_dwordx4 v[14:17], v[14:15], off offset:48
	v_mov_b32_e32 v0, 0x358637bd
	s_add_i32 s14, 0, 0x20000
	s_waitcnt vmcnt(0)
	v_add_f32_e32 v2, v2, v3
	v_add_f32_e32 v3, v4, v5
	v_add_f32_e32 v4, v6, v7
	v_add_f32_e32 v5, v8, v9
	v_add_f32_e32 v6, v10, v11
	v_add_f32_e32 v7, v12, v13
	v_add_f32_e32 v8, v14, v15
	v_add_f32_e32 v9, v16, v17
	v_add_f32_e32 v2, v2, v3
	v_add_f32_e32 v3, v4, v5
	v_add_f32_e32 v4, v6, v7
	v_add_f32_e32 v5, v8, v9
	v_add_f32_e32 v2, v2, v3
	v_add_f32_e32 v3, v4, v5
	v_fmamk_f32 v2, v2, 0x3b000000, v0
	v_fmac_f32_e32 v0, 0x3b000000, v3
	v_div_scale_f32 v3, s[4:5], v2, v2, v0
	v_rcp_f32_e32 v4, v3
	v_div_scale_f32 v5, vcc, v0, v2, v0
	s_mov_b32 s4, 0xf800000
	v_fma_f32 v6, -v3, v4, 1.0
	v_fmac_f32_e32 v4, v6, v4
	v_mul_f32_e32 v6, v5, v4
	v_fma_f32 v7, -v3, v6, v5
	v_fmac_f32_e32 v6, v7, v4
	v_fma_f32 v3, -v3, v6, v5
	v_div_fmas_f32 v3, v3, v4, v6
	v_div_fixup_f32 v2, v3, v2, v0
	v_mul_f32_e32 v3, 0x4f800000, v2
	v_cmp_gt_f32_e32 vcc, s4, v2
	v_mov_b32_e32 v5, 0x260
	s_nop 0
	v_cndmask_b32_e32 v2, v2, v3, vcc
	v_sqrt_f32_e32 v4, v2
	v_rsq_f32_e32 v3, v0
	v_add_u32_e32 v0, -1, v4
	v_add_u32_e32 v6, 1, v4
	v_fma_f32 v7, -v0, v4, v2
	v_fma_f32 v8, -v6, v4, v2
	v_cmp_ge_f32_e64 s[4:5], 0, v7
	s_nop 1
	v_cndmask_b32_e64 v0, v4, v0, s[4:5]
	v_cmp_lt_f32_e64 s[4:5], 0, v8
	s_nop 1
	v_cndmask_b32_e64 v0, v0, v6, s[4:5]
	v_mul_f32_e32 v4, 0x37800000, v0
	v_cndmask_b32_e32 v0, v0, v4, vcc
	v_cmp_class_f32_e32 vcc, v2, v5
	s_nop 1
	v_cndmask_b32_e32 v2, v0, v2, vcc
	v_add_u32_e32 v0, s14, v156
	ds_write_b64 v0, v[2:3] offset:2048
.LBB0_607:
	s_or_b64 exec, exec, s[12:13]
	s_add_u32 s10, s10, s96
	s_addc_u32 s11, s11, s24
	v_mov_b64_e32 v[2:3], 0x407
	v_cmp_gt_i64_e32 vcc, s[10:11], v[2:3]
	s_cbranch_vccnz .LBB0_619
	s_and_saveexec_b64 s[12:13], s[2:3]
	s_cbranch_execz .LBB0_610
	s_ashr_i32 s4, s10, 31
	s_lshr_b32 s4, s4, 29
	s_add_i32 s4, s10, s4
	s_ashr_i32 s5, s4, 3
	s_and_b32 s4, s4, -8
	s_sub_i32 s4, s10, s4
	s_cmp_lt_i32 s4, 0
	s_movk_i32 s14, 0x82
	s_movk_i32 s14, 0x80
	s_mul_i32 s4, s4, s14
	s_add_i32 s4, s4, s5
	s_ashr_i32 s5, s4, 31
	s_lshr_b32 s5, s5, 27
	s_add_i32 s5, s4, s5
	s_ashr_i32 s14, s5, 5
	s_lshl_b32 s14, s14, 3
	s_sub_i32 s15, 0x102, s14
	s_min_i32 s15, s15, 8
	s_abs_i32 s15, s15
	v_cvt_f32_u32_e32 v0, s15
	s_sub_i32 s16, 0, s15
	s_andn2_b32 s5, s5, 31
	s_sub_i32 s4, s4, s5
	v_rcp_iflag_f32_e32 v0, v0
	s_ashr_i32 s5, s4, 31
	s_abs_i32 s4, s4
	v_mul_f32_e32 v0, 0x4f7ffffe, v0
	v_cvt_u32_f32_e32 v0, v0
	s_nop 0
	v_readfirstlane_b32 s17, v0
	s_mul_i32 s16, s16, s17
	s_mul_hi_u32 s16, s17, s16
	s_add_i32 s17, s17, s16
	s_mul_hi_u32 s16, s4, s17
	s_mul_i32 s16, s16, s15
	s_sub_i32 s4, s4, s16
	s_sub_i32 s16, s4, s15
	s_cmp_ge_u32 s4, s15
	s_cselect_b32 s4, s16, s4
	s_sub_i32 s16, s4, s15
	s_cmp_ge_u32 s4, s15
	s_cselect_b32 s4, s16, s4
	s_xor_b32 s4, s4, s5
	s_sub_i32 s4, s4, s5
	s_add_i32 s14, s14, s4
	v_lshl_or_b32 v2, s14, 10, v1
	v_ashrrev_i32_e32 v3, 31, v2
	v_lshl_add_u64 v[14:15], v[2:3], 4, s[8:9]
	global_load_dwordx4 v[2:5], v[14:15], off
	global_load_dwordx4 v[6:9], v[14:15], off offset:16
	global_load_dwordx4 v[10:13], v[14:15], off offset:32
	s_nop 0
	global_load_dwordx4 v[14:17], v[14:15], off offset:48
	v_mov_b32_e32 v0, 0x358637bd
	s_add_i32 s14, 0, 0x20000
	s_waitcnt vmcnt(0)
	v_add_f32_e32 v2, v2, v3
	v_add_f32_e32 v3, v4, v5
	v_add_f32_e32 v4, v6, v7
	v_add_f32_e32 v5, v8, v9
	v_add_f32_e32 v6, v10, v11
	v_add_f32_e32 v7, v12, v13
	v_add_f32_e32 v8, v14, v15
	v_add_f32_e32 v9, v16, v17
	v_add_f32_e32 v2, v2, v3
	v_add_f32_e32 v3, v4, v5
	v_add_f32_e32 v4, v6, v7
	v_add_f32_e32 v5, v8, v9
	v_add_f32_e32 v2, v2, v3
	v_add_f32_e32 v3, v4, v5
	v_fmamk_f32 v2, v2, 0x3b000000, v0
	v_fmac_f32_e32 v0, 0x3b000000, v3
	v_div_scale_f32 v3, s[4:5], v2, v2, v0
	v_rcp_f32_e32 v4, v3
	v_div_scale_f32 v5, vcc, v0, v2, v0
	s_mov_b32 s4, 0xf800000
	v_fma_f32 v6, -v3, v4, 1.0
	v_fmac_f32_e32 v4, v6, v4
	v_mul_f32_e32 v6, v5, v4
	v_fma_f32 v7, -v3, v6, v5
	v_fmac_f32_e32 v6, v7, v4
	v_fma_f32 v3, -v3, v6, v5
	v_div_fmas_f32 v3, v3, v4, v6
	v_div_fixup_f32 v2, v3, v2, v0
	v_mul_f32_e32 v3, 0x4f800000, v2
	v_cmp_gt_f32_e32 vcc, s4, v2
	v_mov_b32_e32 v5, 0x260
	s_nop 0
	v_cndmask_b32_e32 v2, v2, v3, vcc
	v_sqrt_f32_e32 v4, v2
	v_rsq_f32_e32 v3, v0
	v_add_u32_e32 v0, -1, v4
	v_add_u32_e32 v6, 1, v4
	v_fma_f32 v7, -v0, v4, v2
	v_fma_f32 v8, -v6, v4, v2
	v_cmp_ge_f32_e64 s[4:5], 0, v7
	s_nop 1
	v_cndmask_b32_e64 v0, v4, v0, s[4:5]
	v_cmp_lt_f32_e64 s[4:5], 0, v8
	s_nop 1
	v_cndmask_b32_e64 v0, v0, v6, s[4:5]
	v_mul_f32_e32 v4, 0x37800000, v0
	v_cndmask_b32_e32 v0, v0, v4, vcc
	v_cmp_class_f32_e32 vcc, v2, v5
	s_nop 1
	v_cndmask_b32_e32 v2, v0, v2, vcc
	v_add_u32_e32 v0, s14, v156
	ds_write_b64 v0, v[2:3] offset:4096
.LBB0_610:
	s_or_b64 exec, exec, s[12:13]
	s_add_u32 s10, s10, s96
	s_addc_u32 s11, s11, s24
	v_mov_b64_e32 v[2:3], 0x407
	v_cmp_gt_i64_e32 vcc, s[10:11], v[2:3]
	s_cbranch_vccnz .LBB0_619
	s_and_saveexec_b64 s[12:13], s[2:3]
	s_cbranch_execz .LBB0_613
	s_ashr_i32 s4, s10, 31
	s_lshr_b32 s4, s4, 29
	s_add_i32 s4, s10, s4
	s_ashr_i32 s5, s4, 3
	s_and_b32 s4, s4, -8
	s_sub_i32 s4, s10, s4
	s_cmp_lt_i32 s4, 0
	s_movk_i32 s14, 0x82
	s_movk_i32 s14, 0x80
	s_mul_i32 s4, s4, s14
	s_add_i32 s4, s4, s5
	s_ashr_i32 s5, s4, 31
	s_lshr_b32 s5, s5, 27
	s_add_i32 s5, s4, s5
	s_ashr_i32 s14, s5, 5
	s_lshl_b32 s14, s14, 3
	s_sub_i32 s15, 0x102, s14
	s_min_i32 s15, s15, 8
	s_abs_i32 s15, s15
	v_cvt_f32_u32_e32 v0, s15
	s_sub_i32 s16, 0, s15
	s_andn2_b32 s5, s5, 31
	s_sub_i32 s4, s4, s5
	v_rcp_iflag_f32_e32 v0, v0
	s_ashr_i32 s5, s4, 31
	s_abs_i32 s4, s4
	v_mul_f32_e32 v0, 0x4f7ffffe, v0
	v_cvt_u32_f32_e32 v0, v0
	s_nop 0
	v_readfirstlane_b32 s17, v0
	s_mul_i32 s16, s16, s17
	s_mul_hi_u32 s16, s17, s16
	s_add_i32 s17, s17, s16
	s_mul_hi_u32 s16, s4, s17
	s_mul_i32 s16, s16, s15
	s_sub_i32 s4, s4, s16
	s_sub_i32 s16, s4, s15
	s_cmp_ge_u32 s4, s15
	s_cselect_b32 s4, s16, s4
	s_sub_i32 s16, s4, s15
	s_cmp_ge_u32 s4, s15
	s_cselect_b32 s4, s16, s4
	s_xor_b32 s4, s4, s5
	s_sub_i32 s4, s4, s5
	s_add_i32 s14, s14, s4
	v_lshl_or_b32 v2, s14, 10, v1
	v_ashrrev_i32_e32 v3, 31, v2
	v_lshl_add_u64 v[14:15], v[2:3], 4, s[8:9]
	global_load_dwordx4 v[2:5], v[14:15], off
	global_load_dwordx4 v[6:9], v[14:15], off offset:16
	global_load_dwordx4 v[10:13], v[14:15], off offset:32
	s_nop 0
	global_load_dwordx4 v[14:17], v[14:15], off offset:48
	v_mov_b32_e32 v0, 0x358637bd
	s_add_i32 s14, 0, 0x20000
	s_waitcnt vmcnt(0)
	v_add_f32_e32 v2, v2, v3
	v_add_f32_e32 v3, v4, v5
	v_add_f32_e32 v4, v6, v7
	v_add_f32_e32 v5, v8, v9
	v_add_f32_e32 v6, v10, v11
	v_add_f32_e32 v7, v12, v13
	v_add_f32_e32 v8, v14, v15
	v_add_f32_e32 v9, v16, v17
	v_add_f32_e32 v2, v2, v3
	v_add_f32_e32 v3, v4, v5
	v_add_f32_e32 v4, v6, v7
	v_add_f32_e32 v5, v8, v9
	v_add_f32_e32 v2, v2, v3
	v_add_f32_e32 v3, v4, v5
	v_fmamk_f32 v2, v2, 0x3b000000, v0
	v_fmac_f32_e32 v0, 0x3b000000, v3
	v_div_scale_f32 v3, s[4:5], v2, v2, v0
	v_rcp_f32_e32 v4, v3
	v_div_scale_f32 v5, vcc, v0, v2, v0
	s_mov_b32 s4, 0xf800000
	v_fma_f32 v6, -v3, v4, 1.0
	v_fmac_f32_e32 v4, v6, v4
	v_mul_f32_e32 v6, v5, v4
	v_fma_f32 v7, -v3, v6, v5
	v_fmac_f32_e32 v6, v7, v4
	v_fma_f32 v3, -v3, v6, v5
	v_div_fmas_f32 v3, v3, v4, v6
	v_div_fixup_f32 v2, v3, v2, v0
	v_mul_f32_e32 v3, 0x4f800000, v2
	v_cmp_gt_f32_e32 vcc, s4, v2
	v_mov_b32_e32 v5, 0x260
	s_nop 0
	v_cndmask_b32_e32 v2, v2, v3, vcc
	v_sqrt_f32_e32 v4, v2
	v_rsq_f32_e32 v3, v0
	v_add_u32_e32 v0, -1, v4
	v_add_u32_e32 v6, 1, v4
	v_fma_f32 v7, -v0, v4, v2
	v_fma_f32 v8, -v6, v4, v2
	v_cmp_ge_f32_e64 s[4:5], 0, v7
	s_nop 1
	v_cndmask_b32_e64 v0, v4, v0, s[4:5]
	v_cmp_lt_f32_e64 s[4:5], 0, v8
	s_nop 1
	v_cndmask_b32_e64 v0, v0, v6, s[4:5]
	v_mul_f32_e32 v4, 0x37800000, v0
	v_cndmask_b32_e32 v0, v0, v4, vcc
	v_cmp_class_f32_e32 vcc, v2, v5
	s_nop 1
	v_cndmask_b32_e32 v2, v0, v2, vcc
	v_add_u32_e32 v0, s14, v156
	ds_write_b64 v0, v[2:3] offset:6144
.LBB0_613:
	s_or_b64 exec, exec, s[12:13]
	s_add_u32 s4, s10, s96
	s_addc_u32 s5, s11, s24
	v_mov_b64_e32 v[2:3], 0x407
	v_cmp_gt_i64_e32 vcc, s[4:5], v[2:3]
	s_cbranch_vccnz .LBB0_619
	s_and_saveexec_b64 s[10:11], s[2:3]
	s_cbranch_execz .LBB0_616
	s_ashr_i32 s2, s4, 31
	s_lshr_b32 s2, s2, 29
	s_add_i32 s2, s4, s2
	s_ashr_i32 s3, s2, 3
	s_and_b32 s2, s2, -8
	s_sub_i32 s2, s4, s2
	s_lshl_b32 s2, s2, 7
	s_add_i32 s2, s2, s3
	s_cmpk_ge_i32 s4, 0x400
	s_cselect_b32 s2, s4, s2
	s_nop 0
	s_ashr_i32 s3, s2, 31
	s_lshr_b32 s3, s3, 27
	s_add_i32 s3, s2, s3
	s_ashr_i32 s12, s3, 5
	s_lshl_b32 s12, s12, 3
	s_sub_i32 s13, 0x102, s12
	s_min_i32 s13, s13, 8
	s_abs_i32 s13, s13
	v_cvt_f32_u32_e32 v0, s13
	s_sub_i32 s14, 0, s13
	s_andn2_b32 s3, s3, 31
	s_sub_i32 s2, s2, s3
	v_rcp_iflag_f32_e32 v0, v0
	s_ashr_i32 s3, s2, 31
	s_abs_i32 s2, s2
	v_mul_f32_e32 v0, 0x4f7ffffe, v0
	v_cvt_u32_f32_e32 v0, v0
	s_nop 0
	v_readfirstlane_b32 s15, v0
	s_mul_i32 s14, s14, s15
	s_mul_hi_u32 s14, s15, s14
	s_add_i32 s15, s15, s14
	s_mul_hi_u32 s14, s2, s15
	s_mul_i32 s14, s14, s13
	s_sub_i32 s2, s2, s14
	s_sub_i32 s14, s2, s13
	s_cmp_ge_u32 s2, s13
	s_cselect_b32 s2, s14, s2
	s_sub_i32 s14, s2, s13
	s_cmp_ge_u32 s2, s13
	s_cselect_b32 s2, s14, s2
	s_xor_b32 s2, s2, s3
	s_sub_i32 s2, s2, s3
	s_add_i32 s12, s12, s2
	v_lshl_or_b32 v2, s12, 10, v1
	v_ashrrev_i32_e32 v3, 31, v2
	s_waitcnt lgkmcnt(0)
	v_lshl_add_u64 v[18:19], v[2:3], 4, s[8:9]
	global_load_dwordx4 v[2:5], v[18:19], off
	global_load_dwordx4 v[6:9], v[18:19], off offset:16
	global_load_dwordx4 v[10:13], v[18:19], off offset:32
	global_load_dwordx4 v[14:17], v[18:19], off offset:48
	v_mov_b32_e32 v0, 0x358637bd
	s_add_i32 s12, 0, 0x20000
	s_waitcnt vmcnt(0)
	v_add_f32_e32 v2, v2, v3
	v_add_f32_e32 v3, v4, v5
	v_add_f32_e32 v4, v6, v7
	v_add_f32_e32 v5, v8, v9
	v_add_f32_e32 v6, v10, v11
	v_add_f32_e32 v7, v12, v13
	v_add_f32_e32 v8, v14, v15
	v_add_f32_e32 v9, v16, v17
	v_add_f32_e32 v2, v2, v3
	v_add_f32_e32 v3, v4, v5
	v_add_f32_e32 v4, v6, v7
	v_add_f32_e32 v5, v8, v9
	v_add_f32_e32 v2, v2, v3
	v_add_f32_e32 v3, v4, v5
	v_fmamk_f32 v2, v2, 0x3b000000, v0
	v_fmac_f32_e32 v0, 0x3b000000, v3
	v_div_scale_f32 v3, s[2:3], v2, v2, v0
	v_rcp_f32_e32 v4, v3
	v_div_scale_f32 v5, vcc, v0, v2, v0
	s_mov_b32 s2, 0xf800000
	v_fma_f32 v6, -v3, v4, 1.0
	v_fmac_f32_e32 v4, v6, v4
	v_mul_f32_e32 v6, v5, v4
	v_fma_f32 v7, -v3, v6, v5
	v_fmac_f32_e32 v6, v7, v4
	v_fma_f32 v3, -v3, v6, v5
	v_div_fmas_f32 v3, v3, v4, v6
	v_div_fixup_f32 v2, v3, v2, v0
	v_mul_f32_e32 v3, 0x4f800000, v2
	v_cmp_gt_f32_e32 vcc, s2, v2
	v_mov_b32_e32 v5, 0x260
	s_nop 0
	v_cndmask_b32_e32 v2, v2, v3, vcc
	v_sqrt_f32_e32 v4, v2
	v_rsq_f32_e32 v3, v0
	v_add_u32_e32 v0, -1, v4
	v_add_u32_e32 v6, 1, v4
	v_fma_f32 v7, -v0, v4, v2
	v_fma_f32 v8, -v6, v4, v2
	v_cmp_ge_f32_e64 s[2:3], 0, v7
	s_nop 1
	v_cndmask_b32_e64 v0, v4, v0, s[2:3]
	v_cmp_lt_f32_e64 s[2:3], 0, v8
	s_nop 1
	v_cndmask_b32_e64 v0, v0, v6, s[2:3]
	v_mul_f32_e32 v4, 0x37800000, v0
	v_cndmask_b32_e32 v0, v0, v4, vcc
	v_cmp_class_f32_e32 vcc, v2, v5
	s_nop 1
	v_cndmask_b32_e32 v2, v0, v2, vcc
	v_add_u32_e32 v0, s12, v156
	ds_write_b64 v0, v[2:3] offset:8192

.LBB0_619:
	v_cndmask_b32_e64 v0, 0, 1, s[6:7]
	v_cmp_ne_u32_e64 s[0:1], 1, v0
	s_andn2_b64 vcc, exec, s[6:7]
	v_readfirstlane_b32 s2, v188
	s_waitcnt vmcnt(0) lgkmcnt(0)
	s_barrier
	s_cbranch_vccnz .LBB0_621
	s_lshr_b32 s3, s25, 29
	v_readlane_b32 s5, v249, 0
	s_add_i32 s3, s5, s3
	s_ashr_i32 s4, s3, 3
	s_and_b32 s3, s3, -8
	s_sub_i32 s3, s5, s3
	s_cmp_lt_i32 s3, 0
	s_movk_i32 s5, 0x82
	s_movk_i32 s5, 0x80
	s_mul_i32 s3, s3, s5
	s_add_i32 s3, s3, s4
	s_ashr_i32 s4, s3, 31
	s_lshr_b32 s4, s4, 27
	s_add_i32 s4, s3, s4
	s_ashr_i32 s4, s4, 5
	s_lshl_b32 s6, s4, 3
	s_sub_i32 s5, 0x102, s6
	s_lshl_b32 s4, s4, 5
	s_min_u32 s7, s5, 8
	s_sub_i32 s3, s3, s4
	s_sext_i32_i8 s4, s3
	v_cvt_f32_ubyte0_e32 v2, s7
	v_cvt_f32_i32_e32 v0, s4
	v_rcp_iflag_f32_e32 v3, v2
	s_ashr_i32 s4, s4, 30
	s_or_b32 s8, s4, 1
	v_mul_f32_e32 v3, v0, v3
	v_trunc_f32_e32 v3, v3
	v_fma_f32 v0, -v3, v2, v0
	v_cvt_i32_f32_e32 v3, v3
	v_cmp_ge_f32_e64 s[4:5], |v0|, v2
	s_and_b64 s[4:5], s[4:5], exec
	s_cselect_b32 s4, s8, 0
	v_readfirstlane_b32 s5, v3
	s_add_i32 s4, s5, s4
	s_sext_i32_i8 s56, s4
	s_mul_i32 s4, s4, s7
	s_sub_i32 s3, s3, s4
	s_sext_i32_i8 s3, s3
	s_add_i32 s4, s6, s3

.LBB0_624:
	s_add_u32 s10, s30, 0x1a400000
	s_addc_u32 s11, s31, 0
	s_add_u32 s12, s30, 0x100000
	s_addc_u32 s13, s31, 0
	s_lshl_b32 s1, s1, 5
	s_mov_b64 s[14:15], 0x80
	s_and_b32 s20, s1, 0x60
	s_add_i32 m0, s38, 0x18000
	v_lshl_add_u64 v[8:9], v[8:9], 0, s[14:15]
	s_lshl_b32 s3, s0, 13
	s_lshl_b32 s1, s20, 7
	s_waitcnt vmcnt(2)
	s_barrier
	global_load_lds_dwordx4 v[8:9], off
	v_lshl_add_u64 v[6:7], v[6:7], 0, s[14:15]
	s_add_i32 m0, s38, 0x1a000
	s_add_i32 s42, s38, 0x8000
	s_add_i32 s43, s38, 0xa000
	global_load_lds_dwordx4 v[6:7], off
	v_lshl_add_u64 v[2:3], v[2:3], 0, s[14:15]
	s_mov_b32 m0, s42
	s_add_u32 s16, s60, 0x40080
	global_load_lds_dwordx4 v[2:3], off
	v_lshl_add_u64 v[2:3], v[4:5], 0, s[14:15]
	s_mov_b32 m0, s43
	s_addc_u32 s17, s61, 0
	global_load_lds_dwordx4 v[2:3], off
	s_add_i32 m0, s38, 0x1c000
	v_lshl_add_u64 v[2:3], s[16:17], 0, v[134:135]
	global_load_lds_dwordx4 v[2:3], off
	v_lshl_add_u64 v[2:3], s[16:17], 0, v[138:139]
	s_add_i32 m0, s38, 0x1e000
	v_and_b32_e32 v1, 32, v1
	global_load_lds_dwordx4 v[2:3], off
	v_bfe_u32 v3, v188, 4, 2
	v_and_b32_e32 v2, 15, v188
	v_lshlrev_b32_e32 v4, 4, v3
	v_lshl_or_b32 v5, v2, 6, v4
	v_bitop3_b32 v5, v5, s3, v1 bitop3:0xde
	v_lshlrev_b32_e32 v6, 6, v188
	s_movk_i32 s3, 0x3c0
	v_and_or_b32 v4, v6, s3, v4
	s_lshl_b32 s3, s0, 9
	s_cmpk_lt_u32 s2, 0x100
	s_cselect_b64 s[16:17], -1, 0
	s_add_i32 s2, 0, 0x20000
	v_bitop3_b32 v158, s1, v4, v1 bitop3:0xf6
	v_lshlrev_b32_e32 v1, 3, v2
	s_add_i32 s21, s2, s3
	s_add_i32 s3, s3, 0
	v_add_u32_e32 v159, s21, v1
	s_add_i32 s21, s3, 0x20080
	v_add_u32_e32 v160, s21, v1
	s_add_i32 s21, s3, 0x20100
	v_add_u32_e32 v161, s21, v1
	s_add_i32 s21, s3, 0x20180
	v_add_u32_e32 v162, s21, v1
	s_add_i32 s21, s3, 0x20400
	v_add_u32_e32 v163, s21, v1
	s_add_i32 s21, s3, 0x20480
	v_add_u32_e32 v164, s21, v1
	s_add_i32 s21, s3, 0x20500
	s_add_i32 s3, s3, 0x20580
	v_add_u32_e32 v165, s21, v1
	v_add_u32_e32 v166, s3, v1
	v_lshlrev_b32_e32 v1, 8, v188
	v_and_b32_e32 v1, 0x38000, v1
	v_lshlrev_b32_e32 v4, 11, v12
	v_readlane_b32 s64, v249, 1
	v_or3_b32 v1, v10, v1, v4
	v_lshl_or_b32 v157, s0, 6, v2
	v_readlane_b32 s65, v249, 2
	v_add_u32_e32 v2, v1, v11
	v_lshlrev_b32_e32 v1, 4, v13
	v_readlane_b32 s66, v249, 3
	v_readlane_b32 s67, v249, 4
	s_mov_b64 s[52:53], s[64:65]
	v_and_b32_e32 v1, 0x78000, v1
	s_mov_b64 s[18:19], 0x40080
	s_waitcnt vmcnt(6)
	v_cmp_eq_u32_e64 s[0:1], 0, v3
	s_mov_b64 s[54:55], s[66:67]
	v_lshl_or_b32 v168, v3, 3, s20
	v_mov_b32_e32 v3, v0
	v_or3_b32 v1, v10, v1, v4
	s_add_u32 s44, s54, 0xf0000000
	v_lshl_add_u64 v[140:141], v[2:3], 0, s[18:19]
	v_add_u32_e32 v2, v1, v11
	v_lshl_add_u32 v167, v157, 3, s2
	s_addc_u32 s45, s55, -1
	v_lshl_add_u64 v[142:143], v[2:3], 0, s[18:19]
	v_mov_b64_e32 v[144:145], 0x408
	v_mov_b64_e32 v[146:147], 0x407
	s_movk_i32 s46, 0x82
	s_add_i32 s47, 0, 0x10000
	s_add_i32 s48, 0, 0x14000
	v_add_u32_e32 v169, 0, v5
	s_barrier
	v_readlane_b32 s68, v249, 5
	v_readlane_b32 s69, v249, 6
	v_readlane_b32 s70, v249, 7
	v_readlane_b32 s71, v249, 8
	v_readlane_b32 s72, v249, 9
	v_readlane_b32 s73, v249, 10
	v_readlane_b32 s74, v249, 11
	v_readlane_b32 s75, v249, 12
	v_readlane_b32 s76, v249, 13
	v_readlane_b32 s77, v249, 14
	v_readlane_b32 s78, v249, 15
	v_readlane_b32 s79, v249, 16
	s_mov_b32 s98, 0
	s_branch .LBB0_627

.LBB0_627:
	s_add_i32 s49, s5, 1
	s_mul_i32 s2, s49, s24
	s_mul_hi_u32 s3, s49, s96
	s_add_i32 s3, s3, s2
	s_mul_i32 s2, s49, s96
	v_readlane_b32 s19, v249, 0
	s_add_u32 s22, s2, s19
	s_addc_u32 s23, s3, s25
	v_cmp_gt_i64_e32 vcc, s[22:23], v[146:147]
	v_cmp_lt_i64_e64 s[2:3], s[22:23], v[144:145]
	s_cbranch_vccnz .LBB0_629
	s_ashr_i32 s18, s22, 31
	s_lshr_b32 s18, s18, 29
	s_add_i32 s18, s22, s18
	s_ashr_i32 s19, s18, 3
	s_and_b32 s18, s18, -8
	s_sub_i32 s18, s22, s18
	s_lshl_b32 s18, s18, 7
	s_add_i32 s18, s18, s19
	s_cmpk_ge_i32 s22, 0x400
	s_cselect_b32 s18, s22, s18
	s_ashr_i32 s19, s18, 31
	s_lshr_b32 s19, s19, 27
	s_add_i32 s19, s18, s19
	s_ashr_i32 s20, s19, 5
	s_lshl_b32 s20, s20, 3
	s_sub_i32 s21, 0x102, s20
	s_min_i32 s21, s21, 8
	s_abs_i32 s22, s21
	v_cvt_f32_u32_e32 v1, s22
	s_sub_i32 s26, 0, s22
	s_andn2_b32 s19, s19, 31
	s_sub_i32 s19, s18, s19
	v_rcp_iflag_f32_e32 v1, v1
	s_abs_i32 s18, s19
	s_xor_b32 s23, s19, s21
	s_ashr_i32 s23, s23, 31
	v_mul_f32_e32 v1, 0x4f7ffffe, v1
	v_cvt_u32_f32_e32 v1, v1
	s_nop 0
	v_readfirstlane_b32 s27, v1
	s_mul_i32 s26, s26, s27
	s_mul_hi_u32 s26, s27, s26
	s_add_i32 s27, s27, s26
	s_mul_hi_u32 s26, s18, s27
	s_mul_i32 s27, s26, s22
	s_sub_i32 s18, s18, s27
	s_add_i32 s34, s26, 1
	s_sub_i32 s27, s18, s22
	s_cmp_ge_u32 s18, s22
	s_cselect_b32 s26, s34, s26
	s_cselect_b32 s18, s27, s18
	s_add_i32 s27, s26, 1
	s_cmp_ge_u32 s18, s22
	s_cselect_b32 s18, s27, s26
	s_xor_b32 s18, s18, s23
	s_sub_i32 s18, s18, s23
	s_mul_i32 s21, s18, s21
	s_sub_i32 s19, s19, s21
	s_add_i32 s20, s20, s19

.LBB0_683:
	s_or_b64 exec, exec, s[4:5]
	s_andn2_b64 vcc, exec, s[2:3]
	s_mov_b64 s[2:3], -1
	s_cbranch_vccnz .LBB0_626
	s_cmp_lg_u32 s49, 4
	s_cbranch_scc1 .Lea2_skip
	s_cmpk_lg_i32 s96, 0x100
	s_cbranch_scc1 .Lea2_skip
	s_waitcnt vmcnt(0) lgkmcnt(0)
	s_barrier
	s_mov_b32 s98, 1
	v_cmp_eq_u32_e32 vcc, 0, v188
	s_and_saveexec_b64 s[2:3], vcc
	s_cbranch_execz .Lea2_done
	v_mov_b32_e32 v2, 0x23fe0
	ds_read_b32 v3, v2
	ds_read_b32 v4, v2 offset:4
	v_readlane_b32 s4, v249, 20
	v_readlane_b32 s50, v249, 18
	v_readlane_b32 s51, v249, 19
	s_lshl_b32 s4, s4, 8
	s_add_u32 s4, s50, s4
	s_addc_u32 s5, s51, 0
	v_mov_b32_e32 v5, 0x1000
	v_mov_b32_e32 v6, 1
	s_nop 1
	global_atomic_add v6, v5, v6, s[4:5] offset:1024 sc0
	s_waitcnt vmcnt(0) lgkmcnt(0)
	v_add_u32_e32 v6, 1, v6
	v_lshlrev_b32_e32 v7, 2, v3
	v_cmp_eq_u32_e32 vcc, v6, v7
	s_and_saveexec_b64 s[52:53], vcc
	s_cbranch_execz .Lea2_done
	buffer_wbl2 sc1
	s_waitcnt vmcnt(0)
	v_mov_b32_e32 v5, 0x313000
	v_mov_b32_e32 v6, 1
	global_atomic_add v6, v5, v6, s[30:31] offset:1024 sc0
	s_waitcnt vmcnt(0)
	v_add_u32_e32 v6, 1, v6
	v_lshlrev_b32_e32 v7, 2, v4
	v_cmp_eq_u32_e32 vcc, v6, v7
	s_and_saveexec_b64 s[54:55], vcc
	s_cbranch_execz .Lea2_done
	v_mov_b32_e32 v5, 0x313500
	v_mov_b32_e32 v6, 1
	global_atomic_add v5, v6, s[30:31]
	s_waitcnt vmcnt(0)
.Lea2_done:
	s_mov_b64 exec, s[2:3]
.Lea2_skip:
	s_andn2_b64 vcc, exec, s[8:9]
	s_cbranch_vccnz .LBB0_625
	s_barrier
	s_branch .LBB0_625

.LBB0_912:
	s_cmp_lt_i32 s89, 5
	s_cbranch_scc1 .LBB0_962
	s_waitcnt vmcnt(0)
	v_cmp_eq_u32_e32 vcc, 0, v188
	s_barrier
	s_and_saveexec_b64 s[0:1], vcc
	s_cbranch_execz .LBB0_961
	s_cmp_lg_u32 s98, 1
	s_cbranch_scc1 .Lea2_normal
	buffer_wbl2 sc1
	s_waitcnt vmcnt(0) lgkmcnt(0)
	v_mov_b32_e32 v0, 0x310080
	v_mov_b32_e32 v1, 1
	global_atomic_add v0, v1, s[30:31]
	v_mov_b32_e32 v0, 0x313500
.Lea2_wait:
	global_load_dword v1, v0, s[30:31] sc1
	s_waitcnt vmcnt(0)
	v_cmp_ne_u32_e32 vcc, 3, v1
	s_cbranch_vccnz .Lea2_waited
	s_sleep 1
	s_branch .Lea2_wait
.Lea2_waited:
	buffer_inv sc1
	s_waitcnt vmcnt(0)
	s_branch .LBB0_961
.Lea2_normal:
	s_add_i32 s2, 0, 0x23fe0
	v_mov_b32_e32 v0, s2
	s_waitcnt vmcnt(0) expcnt(0) lgkmcnt(0)
	ds_read_b32 v2, v0
	s_add_i32 s2, 0, 0x23fe4
	v_mov_b32_e32 v0, s2
	ds_read_b32 v0, v0
	s_waitcnt lgkmcnt(1)
	v_cmp_ne_u32_e32 vcc, 0, v2
	s_cbranch_vccnz .LBB0_929
	v_readlane_b32 s2, v249, 17
	s_mul_i32 s24, s97, s2
	s_add_u32 s2, s30, 0x310200
	s_addc_u32 s3, s31, 0
	s_add_u32 s4, s30, 0x310400
	s_addc_u32 s5, s31, 0
	s_add_u32 s6, s30, 0x310500
	s_addc_u32 s7, s31, 0
	s_add_u32 s8, s30, 0x310600
	s_addc_u32 s9, s31, 0
	s_add_u32 s10, s30, 0x310700
	s_addc_u32 s11, s31, 0
	s_add_u32 s12, s30, 0x310800
	s_addc_u32 s13, s31, 0
	s_add_u32 s14, s30, 0x310900
	s_addc_u32 s15, s31, 0
	s_add_u32 s16, s30, 0x310a00
	s_addc_u32 s17, s31, 0
	s_add_u32 s18, s30, 0x310b00
	s_addc_u32 s19, s31, 0
	s_add_u32 s20, s30, 0x310c00
	s_addc_u32 s21, s31, 0
	s_add_u32 s22, s30, 0x310d00
	s_addc_u32 s23, s31, 0
	s_add_u32 s34, s30, 0x310e00
	s_addc_u32 s35, s31, 0
	s_add_u32 s36, s30, 0x310f00
	s_addc_u32 s37, s31, 0
	s_add_u32 s38, s30, 0x311000
	s_addc_u32 s39, s31, 0
	s_add_u32 s40, s30, 0x311100
	s_addc_u32 s41, s31, 0
	s_add_u32 s42, s30, 0x311200
	s_addc_u32 s43, s31, 0
	s_add_u32 s44, s30, 0x311300
	s_mul_i32 s24, s24, s96
	s_addc_u32 s45, s31, 0
	s_mov_b32 s25, 1
	v_mov_b32_e32 v16, 0
	s_branch .LBB0_917

.LBB0_962:
	s_mov_b32 s98, 0
	s_cmp_gt_i32 s88, 4
	s_cselect_b64 s[0:1], -1, 0
	s_cmp_lt_i32 s89, 5
	s_cselect_b64 s[2:3], -1, 0
	s_or_b64 s[0:1], s[0:1], s[2:3]
	s_and_b64 vcc, exec, s[0:1]
	s_cbranch_vccnz .LBB0_1037
	v_readlane_b32 s0, v249, 0
	s_cmpk_lg_i32 s96, 0x100
	s_cbranch_scc1 .Lrot_a
	s_sub_u32 s0, s0, 8
	s_and_b32 s0, s0, 0xff
.Lrot_a:
	s_cmpk_gt_i32 s0, 0x162b
	v_readfirstlane_b32 s10, v188
	s_cbranch_scc1 .LBB0_987
	v_readlane_b32 s1, v249, 0
	s_cmpk_lg_i32 s96, 0x100
	s_cbranch_scc1 .Lrot_b
	s_sub_u32 s1, s1, 8
	s_and_b32 s1, s1, 0xff
.Lrot_b:
	s_ashr_i32 s24, s1, 31
	s_lshr_b32 s0, s24, 29
	s_add_i32 s3, s1, s0
	s_and_b32 s0, s3, -8
	s_sub_i32 s4, s1, s0
	s_cmp_gt_i32 s4, 3
	s_cbranch_scc0 .LBB0_966
	s_mul_i32 s0, s4, 0x2c5
	s_add_i32 s2, s0, 4
	s_cbranch_execz .LBB0_967
	s_branch .LBB0_968

.LBB0_973:
	s_add_i32 s42, s42, 1
	s_cmp_lg_u32 s42, 19
	s_cbranch_scc1 .Lg3w_skip
	s_cmpk_lg_i32 s96, 0x100
	s_cbranch_scc1 .Lg3w_skip
	v_readlane_b32 s0, v249, 0
	s_and_b32 s0, s0, 7
	s_cmp_lg_u32 s0, 7
	s_cbranch_scc1 .Lg3w_skip
	v_mov_b32_e32 v4, 0x310080
.Lg3w_spin:
	global_load_dword v5, v4, s[30:31] sc1
	s_waitcnt vmcnt(0)
	v_readfirstlane_b32 s0, v5
	s_cmp_ge_u32 s0, 8
	s_cbranch_scc1 .Lg3w_ok
	s_sleep 1
	s_branch .Lg3w_spin

.Lg3w_skip:
	s_mul_i32 s0, s42, s45
	s_mul_hi_u32 s1, s42, s46
	s_add_i32 s1, s1, s0
	s_mul_i32 s0, s42, s46
	v_readlane_b32 s13, v249, 0
	s_cmpk_lg_i32 s96, 0x100
	s_cbranch_scc1 .Lrot_c
	s_sub_u32 s13, s13, 8
	s_and_b32 s13, s13, 0xff
.Lrot_c:
	s_add_u32 s16, s0, s13
	s_addc_u32 s17, s1, s24
	v_cmp_gt_i64_e32 vcc, s[16:17], v[142:143]
	v_cmp_lt_i64_e64 s[0:1], s[16:17], v[140:141]
	s_cbranch_vccnz .LBB0_979
	s_ashr_i32 s12, s16, 31
	s_lshr_b32 s12, s12, 29
	s_add_i32 s14, s16, s12
	s_and_b32 s12, s14, -8
	s_sub_i32 s15, s16, s12
	s_cmp_gt_i32 s15, 3
	s_mov_b64 s[12:13], -1
	s_cbranch_scc0 .LBB0_976
	s_mul_i32 s12, s15, 0x2c5
	s_add_i32 s16, s12, 4
	s_mov_b64 s[12:13], 0
